# CP1 code placement: GEMM K-loop head on a 64-byte boundary and every 32-MFMA block on an 8-byte phase (3 s_nop pads in load segments), on top of v074
# speedup vs baseline: 1.0056x; 1.0056x over previous
.LBB0_168:
	s_add_u32 s80, s80, 0x80
	s_addc_u32 s81, s81, 0
	s_add_u32 vcc_lo, s34, 0x100
	v_add_u32_e32 v206, 0x10000, v234
	v_add_u32_e32 v207, 0x14000, v234
	v_add_u32_e32 v208, 0x18000, v234
	v_add_u32_e32 v209, 0x1c000, v234
	v_mov_b32_e32 v2, 0
	s_addc_u32 vcc_hi, s35, 0
	s_mov_b32 s34, 0
	v_mov_b32_e32 v3, v2
	v_mov_b32_e32 v4, v2
	v_mov_b32_e32 v5, v2
	v_mov_b32_e32 v6, v2
	v_mov_b32_e32 v7, v2
	v_mov_b32_e32 v8, v2
	v_mov_b32_e32 v9, v2
	v_mov_b32_e32 v18, v2
	v_mov_b32_e32 v19, v2
	v_mov_b32_e32 v20, v2
	v_mov_b32_e32 v21, v2
	v_mov_b32_e32 v22, v2
	v_mov_b32_e32 v23, v2
	v_mov_b32_e32 v24, v2
	v_mov_b32_e32 v25, v2
	v_mov_b32_e32 v34, v2
	v_mov_b32_e32 v35, v2
	v_mov_b32_e32 v36, v2
	v_mov_b32_e32 v37, v2
	v_mov_b32_e32 v38, v2
	v_mov_b32_e32 v39, v2
	v_mov_b32_e32 v40, v2
	v_mov_b32_e32 v41, v2
	v_mov_b32_e32 v50, v2
	v_mov_b32_e32 v51, v2
	v_mov_b32_e32 v52, v2
	v_mov_b32_e32 v53, v2
	v_mov_b32_e32 v54, v2
	v_mov_b32_e32 v55, v2
	v_mov_b32_e32 v56, v2
	v_mov_b32_e32 v57, v2
	v_mov_b32_e32 v10, v2
	v_mov_b32_e32 v11, v2
	v_mov_b32_e32 v12, v2
	v_mov_b32_e32 v13, v2
	v_mov_b32_e32 v14, v2
	v_mov_b32_e32 v15, v2
	v_mov_b32_e32 v16, v2
	v_mov_b32_e32 v17, v2
	v_mov_b32_e32 v26, v2
	v_mov_b32_e32 v27, v2
	v_mov_b32_e32 v28, v2
	v_mov_b32_e32 v29, v2
	v_mov_b32_e32 v30, v2
	v_mov_b32_e32 v31, v2
	v_mov_b32_e32 v32, v2
	v_mov_b32_e32 v33, v2
	v_mov_b32_e32 v42, v2
	v_mov_b32_e32 v43, v2
	v_mov_b32_e32 v44, v2
	v_mov_b32_e32 v45, v2
	v_mov_b32_e32 v46, v2
	v_mov_b32_e32 v47, v2
	v_mov_b32_e32 v48, v2
	v_mov_b32_e32 v49, v2
	v_mov_b32_e32 v58, v2
	v_mov_b32_e32 v59, v2
	v_mov_b32_e32 v60, v2
	v_mov_b32_e32 v61, v2
	v_mov_b32_e32 v62, v2
	v_mov_b32_e32 v63, v2
	v_mov_b32_e32 v64, v2
	v_mov_b32_e32 v65, v2
	v_mov_b32_e32 v66, v2
	v_mov_b32_e32 v67, v2
	v_mov_b32_e32 v68, v2
	v_mov_b32_e32 v69, v2
	v_mov_b32_e32 v70, v2
	v_mov_b32_e32 v71, v2
	v_mov_b32_e32 v72, v2
	v_mov_b32_e32 v73, v2
	v_mov_b32_e32 v82, v2
	v_mov_b32_e32 v83, v2
	v_mov_b32_e32 v84, v2
	v_mov_b32_e32 v85, v2
	v_mov_b32_e32 v86, v2
	v_mov_b32_e32 v87, v2
	v_mov_b32_e32 v88, v2
	v_mov_b32_e32 v89, v2
	v_mov_b32_e32 v98, v2
	v_mov_b32_e32 v99, v2
	v_mov_b32_e32 v100, v2
	v_mov_b32_e32 v101, v2
	v_mov_b32_e32 v106, v2
	v_mov_b32_e32 v107, v2
	v_mov_b32_e32 v108, v2
	v_mov_b32_e32 v109, v2
	v_mov_b32_e32 v110, v2
	v_mov_b32_e32 v111, v2
	v_mov_b32_e32 v112, v2
	v_mov_b32_e32 v113, v2
	v_mov_b32_e32 v114, v2
	v_mov_b32_e32 v115, v2
	v_mov_b32_e32 v116, v2
	v_mov_b32_e32 v117, v2
	v_mov_b32_e32 v74, v2
	v_mov_b32_e32 v75, v2
	v_mov_b32_e32 v76, v2
	v_mov_b32_e32 v77, v2
	v_mov_b32_e32 v78, v2
	v_mov_b32_e32 v79, v2
	v_mov_b32_e32 v80, v2
	v_mov_b32_e32 v81, v2
	v_mov_b32_e32 v90, v2
	v_mov_b32_e32 v91, v2
	v_mov_b32_e32 v92, v2
	v_mov_b32_e32 v93, v2
	v_mov_b32_e32 v94, v2
	v_mov_b32_e32 v95, v2
	v_mov_b32_e32 v96, v2
	v_mov_b32_e32 v97, v2
	v_mov_b32_e32 v102, v2
	v_mov_b32_e32 v103, v2
	v_mov_b32_e32 v104, v2
	v_mov_b32_e32 v105, v2
	v_mov_b32_e32 v118, v2
	v_mov_b32_e32 v119, v2
	v_mov_b32_e32 v120, v2
	v_mov_b32_e32 v121, v2
	v_mov_b32_e32 v122, v2
	v_mov_b32_e32 v123, v2
	v_mov_b32_e32 v124, v2
	v_mov_b32_e32 v125, v2
	v_mov_b32_e32 v126, v2
	v_mov_b32_e32 v127, v2
	v_mov_b32_e32 v128, v2
	v_mov_b32_e32 v129, v2
	.p2align 6
.LBB0_169:
	s_add_i32 s0, s34, 2
	s_add_u32 s1, s80, 0x80
	s_addc_u32 s35, s81, 0
	s_add_i32 s47, 0, 0x10000
	s_cmp_eq_u32 s68, s34
	s_cselect_b32 s35, s43, s35
	s_cselect_b32 s34, s42, s1
	s_cselect_b32 s67, s87, vcc_hi
	s_cselect_b32 s66, s86, vcc_lo
	s_add_i32 s1, 0, 0x14000
	s_waitcnt lgkmcnt(0)
	ds_read_b128 v[130:133], v206
	ds_read_b128 v[134:137], v206 offset:1024
	ds_read_b128 v[138:141], v206 offset:2048
	ds_read_b128 v[142:145], v206 offset:3072
	ds_read_b128 v[146:149], v207
	ds_read_b128 v[150:153], v207 offset:1024
	ds_read_b128 v[154:157], v207 offset:2048
	ds_read_b128 v[158:161], v207 offset:3072
	s_add_i32 m0, s90, 0xc000
	ds_read_b128 v[162:165], v238
	ds_read_b128 v[166:169], v238 offset:1024
	ds_read_b128 v[170:173], v238 offset:2048
	ds_read_b128 v[174:177], v238 offset:3072
	ds_read_b128 v[178:181], v238 offset:4096
	ds_read_b128 v[182:185], v238 offset:5120
	ds_read_b128 v[198:201], v238 offset:6144
	ds_read_b128 v[202:205], v238 offset:7168
	global_load_lds_dwordx4 v194, s[80:81]
	s_add_i32 m0, s90, 0xe000
	s_nop 0
	global_load_lds_dwordx4 v196, s[80:81]
	s_nop 0
	s_waitcnt vmcnt(8)
	s_waitcnt lgkmcnt(0)
	s_barrier
	s_setprio 1
	v_mfma_f32_16x16x32_bf16 v[126:129], v[130:133], v[162:165], v[126:129]
	v_mfma_f32_16x16x32_bf16 v[122:125], v[138:141], v[162:165], v[122:125]
	v_mfma_f32_16x16x32_bf16 v[118:121], v[130:133], v[170:173], v[118:121]
	v_mfma_f32_16x16x32_bf16 v[102:105], v[138:141], v[170:173], v[102:105]
	v_mfma_f32_16x16x32_bf16 v[94:97], v[130:133], v[178:181], v[94:97]
	v_mfma_f32_16x16x32_bf16 v[90:93], v[138:141], v[178:181], v[90:93]
	v_mfma_f32_16x16x32_bf16 v[78:81], v[130:133], v[198:201], v[78:81]
	v_mfma_f32_16x16x32_bf16 v[74:77], v[138:141], v[198:201], v[74:77]
	v_mfma_f32_16x16x32_bf16 v[126:129], v[134:137], v[166:169], v[126:129]
	v_mfma_f32_16x16x32_bf16 v[122:125], v[142:145], v[166:169], v[122:125]
	v_mfma_f32_16x16x32_bf16 v[118:121], v[134:137], v[174:177], v[118:121]
	v_mfma_f32_16x16x32_bf16 v[102:105], v[142:145], v[174:177], v[102:105]
	v_mfma_f32_16x16x32_bf16 v[94:97], v[134:137], v[182:185], v[94:97]
	v_mfma_f32_16x16x32_bf16 v[90:93], v[142:145], v[182:185], v[90:93]
	v_mfma_f32_16x16x32_bf16 v[78:81], v[134:137], v[202:205], v[78:81]
	v_mfma_f32_16x16x32_bf16 v[74:77], v[142:145], v[202:205], v[74:77]
	v_mfma_f32_16x16x32_bf16 v[114:117], v[146:149], v[162:165], v[114:117]
	v_mfma_f32_16x16x32_bf16 v[110:113], v[154:157], v[162:165], v[110:113]
	v_mfma_f32_16x16x32_bf16 v[106:109], v[146:149], v[170:173], v[106:109]
	v_mfma_f32_16x16x32_bf16 v[98:101], v[154:157], v[170:173], v[98:101]
	v_mfma_f32_16x16x32_bf16 v[86:89], v[146:149], v[178:181], v[86:89]
	v_mfma_f32_16x16x32_bf16 v[82:85], v[154:157], v[178:181], v[82:85]
	v_mfma_f32_16x16x32_bf16 v[70:73], v[146:149], v[198:201], v[70:73]
	v_mfma_f32_16x16x32_bf16 v[66:69], v[154:157], v[198:201], v[66:69]
	v_mfma_f32_16x16x32_bf16 v[114:117], v[150:153], v[166:169], v[114:117]
	v_mfma_f32_16x16x32_bf16 v[110:113], v[158:161], v[166:169], v[110:113]
	v_mfma_f32_16x16x32_bf16 v[106:109], v[150:153], v[174:177], v[106:109]
	v_mfma_f32_16x16x32_bf16 v[98:101], v[158:161], v[174:177], v[98:101]
	v_mfma_f32_16x16x32_bf16 v[86:89], v[150:153], v[182:185], v[86:89]
	v_mfma_f32_16x16x32_bf16 v[82:85], v[158:161], v[182:185], v[82:85]
	v_mfma_f32_16x16x32_bf16 v[70:73], v[150:153], v[202:205], v[70:73]
	v_mfma_f32_16x16x32_bf16 v[66:69], v[158:161], v[202:205], v[66:69]
	s_setprio 0
	s_barrier
	s_add_i32 s47, s47, s57
	s_mov_b32 m0, s47
	ds_read_b128 v[162:165], v238 offset:16384
	ds_read_b128 v[166:169], v238 offset:17408
	ds_read_b128 v[170:173], v238 offset:18432
	ds_read_b128 v[174:177], v238 offset:19456
	ds_read_b128 v[178:181], v238 offset:20480
	ds_read_b128 v[182:185], v238 offset:21504
	ds_read_b128 v[198:201], v238 offset:22528
	ds_read_b128 v[202:205], v238 offset:23552
	global_load_lds_dwordx4 v188, s[66:67]
	s_add_i32 m0, s47, 0x2000
	s_add_u32 s100, s66, s69
	s_addc_u32 s101, s67, 0
	s_add_i32 s1, s1, s57
	global_load_lds_dwordx4 v192, s[66:67]
	s_mov_b32 m0, s1
	s_nop 0
	global_load_lds_dwordx4 v188, s[100:101]
	s_add_i32 m0, s1, 0x2000
	s_nop 0
	global_load_lds_dwordx4 v192, s[100:101]
	s_mov_b32 m0, s90
	s_nop 0
	global_load_lds_dwordx4 v186, s[34:35]
	s_mov_b32 m0, s60
	s_nop 0
	global_load_lds_dwordx4 v190, s[34:35]
	s_waitcnt vmcnt(8)
	s_waitcnt lgkmcnt(0)
	s_barrier
	s_setprio 1
	v_mfma_f32_16x16x32_bf16 v[62:65], v[130:133], v[162:165], v[62:65]
	v_mfma_f32_16x16x32_bf16 v[58:61], v[138:141], v[162:165], v[58:61]
	v_mfma_f32_16x16x32_bf16 v[46:49], v[130:133], v[170:173], v[46:49]
	v_mfma_f32_16x16x32_bf16 v[42:45], v[138:141], v[170:173], v[42:45]
	v_mfma_f32_16x16x32_bf16 v[30:33], v[130:133], v[178:181], v[30:33]
	v_mfma_f32_16x16x32_bf16 v[26:29], v[138:141], v[178:181], v[26:29]
	v_mfma_f32_16x16x32_bf16 v[14:17], v[130:133], v[198:201], v[14:17]
	v_mfma_f32_16x16x32_bf16 v[10:13], v[138:141], v[198:201], v[10:13]
	v_mfma_f32_16x16x32_bf16 v[62:65], v[134:137], v[166:169], v[62:65]
	v_mfma_f32_16x16x32_bf16 v[58:61], v[142:145], v[166:169], v[58:61]
	v_mfma_f32_16x16x32_bf16 v[46:49], v[134:137], v[174:177], v[46:49]
	v_mfma_f32_16x16x32_bf16 v[42:45], v[142:145], v[174:177], v[42:45]
	v_mfma_f32_16x16x32_bf16 v[30:33], v[134:137], v[182:185], v[30:33]
	v_mfma_f32_16x16x32_bf16 v[26:29], v[142:145], v[182:185], v[26:29]
	v_mfma_f32_16x16x32_bf16 v[14:17], v[134:137], v[202:205], v[14:17]
	v_mfma_f32_16x16x32_bf16 v[10:13], v[142:145], v[202:205], v[10:13]
	v_mfma_f32_16x16x32_bf16 v[54:57], v[146:149], v[162:165], v[54:57]
	v_mfma_f32_16x16x32_bf16 v[50:53], v[154:157], v[162:165], v[50:53]
	v_mfma_f32_16x16x32_bf16 v[38:41], v[146:149], v[170:173], v[38:41]
	v_mfma_f32_16x16x32_bf16 v[34:37], v[154:157], v[170:173], v[34:37]
	v_mfma_f32_16x16x32_bf16 v[22:25], v[146:149], v[178:181], v[22:25]
	v_mfma_f32_16x16x32_bf16 v[18:21], v[154:157], v[178:181], v[18:21]
	v_mfma_f32_16x16x32_bf16 v[6:9], v[146:149], v[198:201], v[6:9]
	v_mfma_f32_16x16x32_bf16 v[2:5], v[154:157], v[198:201], v[2:5]
	v_mfma_f32_16x16x32_bf16 v[54:57], v[150:153], v[166:169], v[54:57]
	v_mfma_f32_16x16x32_bf16 v[50:53], v[158:161], v[166:169], v[50:53]
	v_mfma_f32_16x16x32_bf16 v[38:41], v[150:153], v[174:177], v[38:41]
	v_mfma_f32_16x16x32_bf16 v[34:37], v[158:161], v[174:177], v[34:37]
	v_mfma_f32_16x16x32_bf16 v[22:25], v[150:153], v[182:185], v[22:25]
	v_mfma_f32_16x16x32_bf16 v[18:21], v[158:161], v[182:185], v[18:21]
	v_mfma_f32_16x16x32_bf16 v[6:9], v[150:153], v[202:205], v[6:9]
	v_mfma_f32_16x16x32_bf16 v[2:5], v[158:161], v[202:205], v[2:5]
	s_setprio 0
	s_barrier
	s_add_i32 s1, 0, 0x18000
	s_add_i32 s47, 0, 0x1c000
	ds_read_b128 v[130:133], v208
	ds_read_b128 v[134:137], v208 offset:1024
	ds_read_b128 v[138:141], v208 offset:2048
	ds_read_b128 v[142:145], v208 offset:3072
	ds_read_b128 v[146:149], v209
	ds_read_b128 v[150:153], v209 offset:1024
	ds_read_b128 v[154:157], v209 offset:2048
	ds_read_b128 v[158:161], v209 offset:3072
	s_mov_b32 m0, s61
	ds_read_b128 v[162:165], v238 offset:32768
	ds_read_b128 v[166:169], v238 offset:33792
	ds_read_b128 v[170:173], v238 offset:34816
	ds_read_b128 v[174:177], v238 offset:35840
	ds_read_b128 v[178:181], v238 offset:36864
	ds_read_b128 v[182:185], v238 offset:37888
	ds_read_b128 v[198:201], v238 offset:38912
	ds_read_b128 v[202:205], v238 offset:39936
	global_load_lds_dwordx4 v194, s[34:35]
	s_mov_b32 m0, s71
	s_nop 0
	global_load_lds_dwordx4 v196, s[34:35]
	s_nop 0
	s_waitcnt vmcnt(8)
	s_waitcnt lgkmcnt(0)
	s_barrier
	s_setprio 1
	v_mfma_f32_16x16x32_bf16 v[126:129], v[130:133], v[162:165], v[126:129]
	v_mfma_f32_16x16x32_bf16 v[122:125], v[138:141], v[162:165], v[122:125]
	v_mfma_f32_16x16x32_bf16 v[118:121], v[130:133], v[170:173], v[118:121]
	v_mfma_f32_16x16x32_bf16 v[102:105], v[138:141], v[170:173], v[102:105]
	v_mfma_f32_16x16x32_bf16 v[94:97], v[130:133], v[178:181], v[94:97]
	v_mfma_f32_16x16x32_bf16 v[90:93], v[138:141], v[178:181], v[90:93]
	v_mfma_f32_16x16x32_bf16 v[78:81], v[130:133], v[198:201], v[78:81]
	v_mfma_f32_16x16x32_bf16 v[74:77], v[138:141], v[198:201], v[74:77]
	v_mfma_f32_16x16x32_bf16 v[126:129], v[134:137], v[166:169], v[126:129]
	v_mfma_f32_16x16x32_bf16 v[122:125], v[142:145], v[166:169], v[122:125]
	v_mfma_f32_16x16x32_bf16 v[118:121], v[134:137], v[174:177], v[118:121]
	v_mfma_f32_16x16x32_bf16 v[102:105], v[142:145], v[174:177], v[102:105]
	v_mfma_f32_16x16x32_bf16 v[94:97], v[134:137], v[182:185], v[94:97]
	v_mfma_f32_16x16x32_bf16 v[90:93], v[142:145], v[182:185], v[90:93]
	v_mfma_f32_16x16x32_bf16 v[78:81], v[134:137], v[202:205], v[78:81]
	v_mfma_f32_16x16x32_bf16 v[74:77], v[142:145], v[202:205], v[74:77]
	v_mfma_f32_16x16x32_bf16 v[114:117], v[146:149], v[162:165], v[114:117]
	v_mfma_f32_16x16x32_bf16 v[110:113], v[154:157], v[162:165], v[110:113]
	v_mfma_f32_16x16x32_bf16 v[106:109], v[146:149], v[170:173], v[106:109]
	v_mfma_f32_16x16x32_bf16 v[98:101], v[154:157], v[170:173], v[98:101]
	v_mfma_f32_16x16x32_bf16 v[86:89], v[146:149], v[178:181], v[86:89]
	v_mfma_f32_16x16x32_bf16 v[82:85], v[154:157], v[178:181], v[82:85]
	v_mfma_f32_16x16x32_bf16 v[70:73], v[146:149], v[198:201], v[70:73]
	v_mfma_f32_16x16x32_bf16 v[66:69], v[154:157], v[198:201], v[66:69]
	v_mfma_f32_16x16x32_bf16 v[114:117], v[150:153], v[166:169], v[114:117]
	v_mfma_f32_16x16x32_bf16 v[110:113], v[158:161], v[166:169], v[110:113]
	v_mfma_f32_16x16x32_bf16 v[106:109], v[150:153], v[174:177], v[106:109]
	v_mfma_f32_16x16x32_bf16 v[98:101], v[158:161], v[174:177], v[98:101]
	v_mfma_f32_16x16x32_bf16 v[86:89], v[150:153], v[182:185], v[86:89]
	v_mfma_f32_16x16x32_bf16 v[82:85], v[158:161], v[182:185], v[82:85]
	v_mfma_f32_16x16x32_bf16 v[70:73], v[150:153], v[202:205], v[70:73]
	v_mfma_f32_16x16x32_bf16 v[66:69], v[158:161], v[202:205], v[66:69]
	s_setprio 0
	s_barrier
	s_add_i32 s1, s1, s57
	s_add_u32 s66, s66, 0x80
	s_addc_u32 s67, s67, 0
	s_add_u32 s100, s100, 0x80
	s_addc_u32 s101, s101, 0
	s_add_u32 s34, s34, 0x80
	s_addc_u32 s35, s35, 0
	s_mov_b32 m0, s1
	ds_read_b128 v[162:165], v238 offset:49152
	ds_read_b128 v[166:169], v238 offset:50176
	ds_read_b128 v[170:173], v238 offset:51200
	ds_read_b128 v[174:177], v238 offset:52224
	ds_read_b128 v[178:181], v238 offset:53248
	ds_read_b128 v[182:185], v238 offset:54272
	ds_read_b128 v[198:201], v238 offset:55296
	ds_read_b128 v[202:205], v238 offset:56320
	global_load_lds_dwordx4 v188, s[66:67]
	s_add_i32 m0, s1, 0x2000
	s_add_i32 s1, s47, s57
	global_load_lds_dwordx4 v192, s[66:67]
	s_mov_b32 m0, s1
	s_nop 0
	global_load_lds_dwordx4 v188, s[100:101]
	s_add_i32 m0, s1, 0x2000
	s_nop 0
	global_load_lds_dwordx4 v192, s[100:101]
	s_mov_b32 m0, s64
	s_nop 0
	global_load_lds_dwordx4 v186, s[34:35]
	s_mov_b32 m0, s65
	s_nop 0
	global_load_lds_dwordx4 v190, s[34:35]
	s_nop 0
	s_waitcnt vmcnt(8)
	s_waitcnt lgkmcnt(0)
	s_barrier
	s_setprio 1
	v_mfma_f32_16x16x32_bf16 v[62:65], v[130:133], v[162:165], v[62:65]
	v_mfma_f32_16x16x32_bf16 v[58:61], v[138:141], v[162:165], v[58:61]
	v_mfma_f32_16x16x32_bf16 v[46:49], v[130:133], v[170:173], v[46:49]
	v_mfma_f32_16x16x32_bf16 v[42:45], v[138:141], v[170:173], v[42:45]
	v_mfma_f32_16x16x32_bf16 v[30:33], v[130:133], v[178:181], v[30:33]
	v_mfma_f32_16x16x32_bf16 v[26:29], v[138:141], v[178:181], v[26:29]
	v_mfma_f32_16x16x32_bf16 v[14:17], v[130:133], v[198:201], v[14:17]
	v_mfma_f32_16x16x32_bf16 v[10:13], v[138:141], v[198:201], v[10:13]
	v_mfma_f32_16x16x32_bf16 v[62:65], v[134:137], v[166:169], v[62:65]
	v_mfma_f32_16x16x32_bf16 v[58:61], v[142:145], v[166:169], v[58:61]
	v_mfma_f32_16x16x32_bf16 v[46:49], v[134:137], v[174:177], v[46:49]
	v_mfma_f32_16x16x32_bf16 v[42:45], v[142:145], v[174:177], v[42:45]
	v_mfma_f32_16x16x32_bf16 v[30:33], v[134:137], v[182:185], v[30:33]
	v_mfma_f32_16x16x32_bf16 v[26:29], v[142:145], v[182:185], v[26:29]
	v_mfma_f32_16x16x32_bf16 v[14:17], v[134:137], v[202:205], v[14:17]
	v_mfma_f32_16x16x32_bf16 v[10:13], v[142:145], v[202:205], v[10:13]
	v_mfma_f32_16x16x32_bf16 v[54:57], v[146:149], v[162:165], v[54:57]
	v_mfma_f32_16x16x32_bf16 v[50:53], v[154:157], v[162:165], v[50:53]
	v_mfma_f32_16x16x32_bf16 v[38:41], v[146:149], v[170:173], v[38:41]
	v_mfma_f32_16x16x32_bf16 v[34:37], v[154:157], v[170:173], v[34:37]
	v_mfma_f32_16x16x32_bf16 v[22:25], v[146:149], v[178:181], v[22:25]
	v_mfma_f32_16x16x32_bf16 v[18:21], v[154:157], v[178:181], v[18:21]
	v_mfma_f32_16x16x32_bf16 v[6:9], v[146:149], v[198:201], v[6:9]
	v_mfma_f32_16x16x32_bf16 v[2:5], v[154:157], v[198:201], v[2:5]
	v_mfma_f32_16x16x32_bf16 v[54:57], v[150:153], v[166:169], v[54:57]
	v_mfma_f32_16x16x32_bf16 v[50:53], v[158:161], v[166:169], v[50:53]
	v_mfma_f32_16x16x32_bf16 v[38:41], v[150:153], v[174:177], v[38:41]
	v_mfma_f32_16x16x32_bf16 v[34:37], v[158:161], v[174:177], v[34:37]
	v_mfma_f32_16x16x32_bf16 v[22:25], v[150:153], v[182:185], v[22:25]
	v_mfma_f32_16x16x32_bf16 v[18:21], v[158:161], v[182:185], v[18:21]
	v_mfma_f32_16x16x32_bf16 v[6:9], v[150:153], v[202:205], v[6:9]
	v_mfma_f32_16x16x32_bf16 v[2:5], v[158:161], v[202:205], v[2:5]
	s_setprio 0
	s_barrier
	s_add_u32 s80, s80, 0x100
	s_addc_u32 s81, s81, 0
	s_add_u32 vcc_lo, vcc_lo, 0x100
	s_addc_u32 vcc_hi, vcc_hi, 0
	s_cmp_ge_u32 s0, s91
	s_mov_b32 s34, s0
	s_cbranch_scc0 .LBB0_169
	v_readlane_b32 s0, v243, 28
	v_readlane_b32 s1, v243, 29
	s_and_b64 vcc, exec, s[0:1]
	s_cbranch_vccz .LBB0_174
	s_barrier
	v_lshl_add_u32 v198, s99, 8, v1
	s_cmp_lt_i32 s70, 1
	s_mov_b64 s[34:35], -1
	s_cbranch_scc0 .LBB0_175
